# GEMM phases: hipcc's per-block s_setprio flips deleted, one static s_setprio 1 for waves 0-3 per GEMM phase (reset at phase end)
# speedup vs baseline: 1.0219x; 1.0046x over previous
.LBB0_207:
.LBB0_208:
	s_cmp_lt_i32 s68, 3
	s_cselect_b64 s[8:9], -1, 0
	s_and_b64 s[8:9], s[8:9], s[6:7]
	s_andn2_b64 vcc, exec, s[8:9]
	v_writelane_b32 v240, s0, 22
	s_nop 1
	v_writelane_b32 v240, s1, 23
	s_cbranch_vccnz .LBB0_225
	v_cmp_gt_u32_e32 vcc, 0x100, v1
	s_cbranch_vccz .Lgprio_3
	s_setprio 1
.Lgprio_3:
	s_cmpk_lg_u32 s70, 0x100
	s_cbranch_scc1 .Lp2_tiles
	s_bitcmp1_b32 s2, 3
	s_cbranch_scc1 .Lpf_begin
.Lp2_tiles:
	s_cmpk_gt_i32 s2, 0x2ff
	v_readfirstlane_b32 s7, v1
	s_cbranch_scc1 .LBB0_225
	v_lshrrev_b32_e32 v4, 1, v1
	v_and_b32_e32 v13, 24, v4
	v_lshrrev_b32_e32 v4, 5, v1
	v_and_b32_e32 v4, 4, v4
	v_bfe_u32 v5, v1, 2, 2
	s_add_u32 s33, s66, 0xa00000
	v_lshlrev_b32_e32 v2, 4, v1
	v_and_b32_e32 v3, 32, v1
	v_bfe_u32 v12, v1, 2, 4
	v_or3_b32 v4, v4, v5, v13
	v_lshrrev_b32_e32 v5, 3, v1
	s_movk_i32 s6, 0x70
	s_addc_u32 s46, s67, 0
	v_bitop3_b32 v10, v2, v3, 48 bitop3:0x6c
	v_and_b32_e32 v11, 64, v1
	v_and_or_b32 v6, v5, s6, v12
	s_movk_i32 s6, 0x60
	v_add_u32_e32 v14, 0x2000, v2
	s_add_u32 s47, s66, 0x1c00000
	v_or_b32_e32 v3, v10, v11
	v_and_or_b32 v5, v5, s6, v4
	v_lshrrev_b32_e32 v2, 7, v14
	s_movk_i32 s6, 0xf0
	s_addc_u32 s58, s67, 0
	v_lshl_or_b32 v132, v5, 11, v3
	v_and_or_b32 v5, v2, s6, v12
	s_movk_i32 s6, 0xe0
	s_ashr_i32 s60, s2, 31
	v_and_or_b32 v2, v2, s6, v4
	s_lshr_b32 s6, s60, 29
	s_add_i32 s6, s2, s6
	s_lshr_b32 s14, s7, 6
	s_ashr_i32 s10, s6, 3
	s_and_b32 s6, s6, -8
	s_lshr_b32 s16, s7, 8
	s_lshl_b32 s59, s14, 10
	s_sub_i32 s6, s2, s6
	s_cmp_lt_i32 s6, 0
	s_movk_i32 s61, 0x61
	s_cselect_b32 s11, s61, 0x60
	s_mul_i32 s6, s6, s11
	s_add_i32 s6, s6, s10
	s_ashr_i32 s10, s6, 31
	s_lshr_b32 s10, s10, 24
	s_add_i32 s10, s6, s10
	s_ashr_i32 s11, s10, 8
	s_and_b32 s10, s10, 0xffffff00
	s_sub_i32 s10, s6, s10
	s_sext_i32_i16 s6, s10
	s_bfe_u32 s6, s6, 0x2001d
	s_add_i32 s12, s10, s6
	s_sext_i32_i16 s6, s12
	s_and_b32 s12, s12, 0xfffc
	s_sub_i32 s10, s10, s12
	s_lshl_b32 s11, s11, 2
	s_sext_i32_i16 s10, s10
	s_add_i32 s28, s11, s10
	s_ashr_i32 s29, s28, 31
	s_lshr_b32 s6, s6, 2
	s_lshl_b64 s[10:11], s[28:29], 19
	s_add_u32 s42, s33, s10
	s_addc_u32 s43, s46, s11
	s_bfe_i64 s[10:11], s[6:7], 0x100000
	s_lshl_b64 s[10:11], s[10:11], 19
	s_add_u32 s48, s47, s10
	s_addc_u32 s49, s58, s11
	s_add_i32 s29, s59, 0
	s_add_i32 m0, s29, 0x10000
	v_lshl_or_b32 v136, v2, 11, v3
	global_load_lds_dwordx4 v132, s[48:49]
	s_add_i32 m0, s29, 0x12000
	s_add_u32 s10, s48, 0x40000
	global_load_lds_dwordx4 v136, s[48:49]
	s_addc_u32 s11, s49, 0
	s_add_i32 m0, s29, 0x14000
	s_add_i32 s62, s29, 0x2000
	global_load_lds_dwordx4 v132, s[10:11]
	s_add_i32 m0, s29, 0x16000
	v_lshl_or_b32 v130, v6, 11, v3
	global_load_lds_dwordx4 v136, s[10:11]
	s_mov_b32 m0, s29
	s_add_u32 s10, s42, 0x40000
	v_lshl_or_b32 v134, v5, 11, v3
	global_load_lds_dwordx4 v130, s[42:43]
	s_mov_b32 m0, s62
	s_addc_u32 s11, s43, 0
	s_add_i32 s63, s29, 0x4000
	global_load_lds_dwordx4 v134, s[42:43]
	s_mov_b32 m0, s63
	s_add_i32 s74, s29, 0x6000
	global_load_lds_dwordx4 v130, s[10:11]
	s_mov_b32 m0, s74
	v_mov_b32_e32 v133, 0
	global_load_lds_dwordx4 v134, s[10:11]
	v_mov_b32_e32 v137, v133
	v_mov_b32_e32 v131, v133
	v_mov_b32_e32 v135, v133
	s_cmp_eq_u32 s16, 1
	s_mov_b32 s75, 0
	v_lshl_add_u64 v[8:9], s[48:49], 0, v[132:133]
	v_lshl_add_u64 v[6:7], s[48:49], 0, v[136:137]
	v_lshl_add_u64 v[2:3], s[42:43], 0, v[130:131]
	s_cselect_b64 s[10:11], -1, 0
	s_cmp_lg_u32 s16, 1
	v_lshl_add_u64 v[4:5], s[42:43], 0, v[134:135]
	s_cbranch_scc1 .LBB0_212
	s_barrier

.Lpf_done:
.LBB0_225:
	s_setprio 0
	s_cmp_gt_i32 s69, 3
	s_cselect_b64 s[6:7], -1, 0
	s_and_b64 s[8:9], s[8:9], s[6:7]
	s_andn2_b64 vcc, exec, s[8:9]
	s_cbranch_vccnz .LBB0_293
	s_cmpk_lt_u32 s69, 0x3e9
	s_mov_b64 s[8:9], -1
	s_cbranch_scc0 .LBB0_280
	s_waitcnt vmcnt(0)
	s_waitcnt vmcnt(0)
	s_barrier
	s_mov_b64 s[8:9], exec
	v_readlane_b32 s10, v240, 4
	v_readlane_b32 s11, v240, 5
	s_and_b64 s[10:11], s[8:9], s[10:11]
	s_mov_b64 exec, s[10:11]
	s_cbranch_execz .LBB0_279
	s_add_i32 s10, 0, 0x26000
	v_mov_b32_e32 v2, s10
	s_waitcnt vmcnt(0) expcnt(0) lgkmcnt(0)
	ds_read_b32 v4, v2
	s_add_i32 s10, 0, 0x26004
	v_mov_b32_e32 v2, s10
	ds_read_b32 v2, v2
	s_waitcnt lgkmcnt(1)
	v_cmp_ne_u32_e32 vcc, 0, v4
	s_cbranch_vccnz .LBB0_243
	s_load_dword s10, s[0:1], 0x110
	s_mov_b32 s44, 1
	v_mov_b32_e32 v18, 0
	s_waitcnt lgkmcnt(0)
	s_mul_i32 s33, s71, s10
	s_add_u32 s10, s66, 0x1bc0200
	s_addc_u32 s11, s67, 0
	s_add_u32 s12, s66, 0x1bc0400
	s_addc_u32 s13, s67, 0
	s_add_u32 s14, s66, 0x1bc0500
	s_addc_u32 s15, s67, 0
	s_add_u32 s16, s66, 0x1bc0600
	s_addc_u32 s17, s67, 0
	s_add_u32 s18, s66, 0x1bc0700
	s_addc_u32 s19, s67, 0
	s_add_u32 s20, s66, 0x1bc0800
	s_addc_u32 s21, s67, 0
	s_add_u32 s22, s66, 0x1bc0900
	s_addc_u32 s23, s67, 0
	s_add_u32 s24, s66, 0x1bc0a00
	s_addc_u32 s25, s67, 0
	s_add_u32 s26, s66, 0x1bc0b00
	s_addc_u32 s27, s67, 0
	s_add_u32 s28, s66, 0x1bc0c00
	s_addc_u32 s29, s67, 0
	s_add_u32 s30, s66, 0x1bc0d00
	s_addc_u32 s31, s67, 0
	s_add_u32 s34, s66, 0x1bc0e00
	s_addc_u32 s35, s67, 0
	s_add_u32 s36, s66, 0x1bc0f00
	s_addc_u32 s37, s67, 0
	s_add_u32 s38, s66, 0x1bc1000
	s_addc_u32 s39, s67, 0
	s_add_u32 s40, s66, 0x1bc1100
	s_addc_u32 s41, s67, 0
	s_add_u32 s42, s66, 0x1bc1200
	s_addc_u32 s43, s67, 0
	s_add_u32 s48, s66, 0x1bc1300
	s_mul_i32 s33, s33, s70
	s_addc_u32 s49, s67, 0
	s_branch .LBB0_231

.LBB0_577:
.LBB0_578:
	s_cmp_lt_i32 s68, 5
	s_cselect_b64 s[6:7], -1, 0
	v_readlane_b32 s72, v240, 0
	s_and_b64 s[14:15], s[6:7], s[4:5]
	v_readlane_b32 s73, v240, 1
	s_andn2_b64 vcc, exec, s[14:15]
	s_cbranch_vccnz .LBB0_629
	v_cmp_gt_u32_e32 vcc, 0x100, v1
	s_cbranch_vccz .Lgprio_5
	s_setprio 1

.LBB0_629:
	s_setprio 0
	s_cmp_gt_i32 s69, 5
	v_readlane_b32 s0, v240, 22
	s_cselect_b64 s[4:5], -1, 0
	v_readlane_b32 s1, v240, 23
	s_and_b64 s[6:7], s[14:15], s[4:5]
	s_load_dwordx16 s[8:23], s[0:1], 0x0
	s_andn2_b64 vcc, exec, s[6:7]
	s_mov_b64 s[96:97], s[72:73]
	s_waitcnt lgkmcnt(0)
	s_mov_b64 s[56:57], s[12:13]
	s_cbranch_vccnz .LBB0_697
	s_cmpk_lt_u32 s69, 0x3e9
	s_mov_b64 s[6:7], -1
	s_cbranch_scc0 .LBB0_684
	s_waitcnt vmcnt(0)
	s_waitcnt vmcnt(0)
	s_barrier
	s_mov_b64 s[6:7], exec
	v_readlane_b32 s8, v240, 4
	v_readlane_b32 s9, v240, 5
	s_and_b64 s[8:9], s[6:7], s[8:9]
	s_mov_b64 exec, s[8:9]
	s_cbranch_execz .LBB0_683
	s_add_i32 s8, 0, 0x26000
	v_mov_b32_e32 v2, s8
	s_waitcnt vmcnt(0) expcnt(0) lgkmcnt(0)
	ds_read_b32 v4, v2
	s_add_i32 s8, 0, 0x26004
	v_mov_b32_e32 v2, s8
	ds_read_b32 v2, v2
	s_waitcnt lgkmcnt(1)
	v_cmp_ne_u32_e32 vcc, 0, v4
	s_cbranch_vccnz .LBB0_647
	s_load_dword s8, s[0:1], 0x110
	s_mov_b32 s44, 1
	v_mov_b32_e32 v18, 0
	s_waitcnt lgkmcnt(0)
	s_mul_i32 s33, s71, s8
	s_add_u32 s8, s66, 0x1bc0200
	s_addc_u32 s9, s67, 0
	s_add_u32 s10, s66, 0x1bc0400
	s_addc_u32 s11, s67, 0
	s_add_u32 s12, s66, 0x1bc0500
	s_addc_u32 s13, s67, 0
	s_add_u32 s14, s66, 0x1bc0600
	s_addc_u32 s15, s67, 0
	s_add_u32 s16, s66, 0x1bc0700
	s_addc_u32 s17, s67, 0
	s_add_u32 s18, s66, 0x1bc0800
	s_addc_u32 s19, s67, 0
	s_add_u32 s20, s66, 0x1bc0900
	s_addc_u32 s21, s67, 0
	s_add_u32 s22, s66, 0x1bc0a00
	s_addc_u32 s23, s67, 0
	s_add_u32 s24, s66, 0x1bc0b00
	s_addc_u32 s25, s67, 0
	s_add_u32 s26, s66, 0x1bc0c00
	s_addc_u32 s27, s67, 0
	s_add_u32 s28, s66, 0x1bc0d00
	s_addc_u32 s29, s67, 0
	s_add_u32 s30, s66, 0x1bc0e00
	s_addc_u32 s31, s67, 0
	s_add_u32 s34, s66, 0x1bc0f00
	s_addc_u32 s35, s67, 0
	s_add_u32 s36, s66, 0x1bc1000
	s_addc_u32 s37, s67, 0
	s_add_u32 s38, s66, 0x1bc1100
	s_addc_u32 s39, s67, 0
	s_add_u32 s40, s66, 0x1bc1200
	s_addc_u32 s41, s67, 0
	s_add_u32 s42, s66, 0x1bc1300
	s_mul_i32 s33, s33, s70
	s_addc_u32 s43, s67, 0
	s_branch .LBB0_635

.LBB0_1081:
	s_cmp_lt_i32 s68, 10
	s_cselect_b64 s[6:7], -1, 0
	s_and_b64 s[8:9], s[6:7], s[4:5]
	s_andn2_b64 vcc, exec, s[8:9]
	s_cbranch_vccnz .LBB0_1170
	v_cmp_gt_u32_e32 vcc, 0x100, v1
	s_cbranch_vccz .Lgprio_10
	s_setprio 1

.LBB0_1170:
	s_setprio 0
	s_cmp_gt_i32 s69, 10
	s_cselect_b64 s[4:5], -1, 0
	s_and_b64 s[6:7], s[8:9], s[4:5]
	s_andn2_b64 vcc, exec, s[6:7]
	s_cbranch_vccnz .LBB0_1238
	s_cmpk_lt_u32 s69, 0x3e9
	s_mov_b64 s[6:7], -1
	s_cbranch_scc0 .LBB0_1225
	s_waitcnt vmcnt(0)
	s_waitcnt vmcnt(0)
	s_barrier
	s_mov_b64 s[6:7], exec
	v_readlane_b32 s8, v240, 4
	v_readlane_b32 s9, v240, 5
	s_and_b64 s[8:9], s[6:7], s[8:9]
	s_mov_b64 exec, s[8:9]
	s_cbranch_execz .LBB0_1224
	s_add_i32 s8, 0, 0x26000
	v_mov_b32_e32 v2, s8
	s_waitcnt vmcnt(0) expcnt(0) lgkmcnt(0)
	ds_read_b32 v4, v2
	s_add_i32 s8, 0, 0x26004
	v_mov_b32_e32 v2, s8
	ds_read_b32 v2, v2
	s_waitcnt lgkmcnt(1)
	v_cmp_ne_u32_e32 vcc, 0, v4
	s_cbranch_vccnz .LBB0_1188
	s_load_dword s8, s[0:1], 0x110
	s_mov_b32 s44, 1
	v_mov_b32_e32 v18, 0
	s_waitcnt lgkmcnt(0)
	s_mul_i32 s33, s71, s8
	s_add_u32 s8, s66, 0x1bc0200
	s_addc_u32 s9, s67, 0
	s_add_u32 s10, s66, 0x1bc0400
	s_addc_u32 s11, s67, 0
	s_add_u32 s12, s66, 0x1bc0500
	s_addc_u32 s13, s67, 0
	s_add_u32 s14, s66, 0x1bc0600
	s_addc_u32 s15, s67, 0
	s_add_u32 s16, s66, 0x1bc0700
	s_addc_u32 s17, s67, 0
	s_add_u32 s18, s66, 0x1bc0800
	s_addc_u32 s19, s67, 0
	s_add_u32 s20, s66, 0x1bc0900
	s_addc_u32 s21, s67, 0
	s_add_u32 s22, s66, 0x1bc0a00
	s_addc_u32 s23, s67, 0
	s_add_u32 s24, s66, 0x1bc0b00
	s_addc_u32 s25, s67, 0
	s_add_u32 s26, s66, 0x1bc0c00
	s_addc_u32 s27, s67, 0
	s_add_u32 s28, s66, 0x1bc0d00
	s_addc_u32 s29, s67, 0
	s_add_u32 s30, s66, 0x1bc0e00
	s_addc_u32 s31, s67, 0
	s_add_u32 s34, s66, 0x1bc0f00
	s_addc_u32 s35, s67, 0
	s_add_u32 s36, s66, 0x1bc1000
	s_addc_u32 s37, s67, 0
	s_add_u32 s38, s66, 0x1bc1100
	s_addc_u32 s39, s67, 0
	s_add_u32 s40, s66, 0x1bc1200
	s_addc_u32 s41, s67, 0
	s_add_u32 s42, s66, 0x1bc1300
	s_mul_i32 s33, s33, s70
	s_addc_u32 s43, s67, 0
	s_branch .LBB0_1176

.LBB0_1238:
	s_cmp_lt_i32 s68, 11
	s_cselect_b64 s[6:7], -1, 0
	s_and_b64 s[24:25], s[6:7], s[4:5]
	s_andn2_b64 vcc, exec, s[24:25]
	s_cbranch_vccnz .LBB0_1293
	v_cmp_gt_u32_e32 vcc, 0x100, v1
	s_cbranch_vccz .Lgprio_11
	s_setprio 1
.Lgprio_11:
	s_add_u32 s33, s66, 0x3c00000
	s_addc_u32 s37, s67, 0
	s_add_u32 s46, s66, 0x1800000
	s_addc_u32 s47, s67, 0
	s_cmpk_lt_i32 s2, 0x100
	s_cselect_b64 s[4:5], -1, 0
	s_cmpk_gt_i32 s2, 0xff
	v_readfirstlane_b32 s8, v1
	s_cbranch_scc1 .LBB0_1241
	s_ashr_i32 s6, s2, 31
	s_lshr_b32 s6, s6, 29
	s_add_i32 s6, s2, s6
	s_ashr_i32 s7, s6, 3
	s_and_b32 s6, s6, -8
	s_sub_i32 s6, s2, s6
	s_lshl_b32 s10, s6, 5
	s_mul_i32 s9, s6, 33
	s_cmp_lt_i32 s6, 0
	s_cselect_b32 s6, s9, s10
	s_add_i32 s6, s6, s7
	s_ashr_i32 s7, s6, 31
	s_lshr_b32 s7, s7, 28
	s_add_i32 s7, s6, s7
	s_ashr_i32 s9, s7, 4
	s_and_b32 s7, s7, -16
	s_sub_i32 s6, s6, s7
	s_bfe_i32 s7, s6, 0x80000
	s_bfe_u32 s7, s7, 0x2000d
	s_add_i32 s7, s6, s7
	s_bfe_i32 s10, s7, 0x80000
	s_and_b32 s7, s7, 0xfc
	s_sub_i32 s6, s6, s7
	s_lshl_b32 s9, s9, 2
	s_sext_i32_i8 s6, s6
	s_add_i32 s6, s9, s6
	s_sext_i32_i16 s11, s10
	s_ashr_i32 s7, s6, 31
	s_lshr_b32 s10, s11, 2
	s_ashr_i32 s18, s11, 2
	s_lshl_b64 s[12:13], s[6:7], 19
	s_add_u32 s12, s33, s12
	s_addc_u32 s13, s37, s13
	s_bfe_i64 s[10:11], s[10:11], 0x100000
	s_lshl_b64 s[10:11], s[10:11], 19
	s_add_u32 s14, s46, s10
	s_addc_u32 s15, s47, s11
	s_andn2_b64 vcc, exec, s[4:5]
	s_cbranch_vccz .LBB0_1242
	s_branch .LBB0_1293

.LBB0_1293:
	s_setprio 0
	s_cmp_gt_i32 s69, 11
	s_cselect_b64 s[4:5], -1, 0
	s_and_b64 s[6:7], s[24:25], s[4:5]
	s_andn2_b64 vcc, exec, s[6:7]
	s_cbranch_vccnz .LBB0_1361
	s_cmpk_lt_u32 s69, 0x3e9
	s_mov_b64 s[6:7], -1
	s_cbranch_scc0 .LBB0_1348
	s_waitcnt vmcnt(0)
	s_waitcnt vmcnt(0)
	s_barrier
	s_mov_b64 s[6:7], exec
	v_readlane_b32 s8, v240, 4
	v_readlane_b32 s9, v240, 5
	s_and_b64 s[8:9], s[6:7], s[8:9]
	s_mov_b64 exec, s[8:9]
	s_cbranch_execz .LBB0_1347
	s_add_i32 s8, 0, 0x26000
	v_mov_b32_e32 v2, s8
	s_waitcnt vmcnt(0) expcnt(0) lgkmcnt(0)
	ds_read_b32 v4, v2
	s_add_i32 s8, 0, 0x26004
	v_mov_b32_e32 v2, s8
	ds_read_b32 v2, v2
	s_waitcnt lgkmcnt(1)
	v_cmp_ne_u32_e32 vcc, 0, v4
	s_cbranch_vccnz .LBB0_1311
	s_load_dword s8, s[0:1], 0x110
	s_mov_b32 s44, 1
	v_mov_b32_e32 v18, 0
	s_waitcnt lgkmcnt(0)
	s_mul_i32 s33, s71, s8
	s_add_u32 s8, s66, 0x1bc0200
	s_addc_u32 s9, s67, 0
	s_add_u32 s10, s66, 0x1bc0400
	s_addc_u32 s11, s67, 0
	s_add_u32 s12, s66, 0x1bc0500
	s_addc_u32 s13, s67, 0
	s_add_u32 s14, s66, 0x1bc0600
	s_addc_u32 s15, s67, 0
	s_add_u32 s16, s66, 0x1bc0700
	s_addc_u32 s17, s67, 0
	s_add_u32 s18, s66, 0x1bc0800
	s_addc_u32 s19, s67, 0
	s_add_u32 s20, s66, 0x1bc0900
	s_addc_u32 s21, s67, 0
	s_add_u32 s22, s66, 0x1bc0a00
	s_addc_u32 s23, s67, 0
	s_add_u32 s24, s66, 0x1bc0b00
	s_addc_u32 s25, s67, 0
	s_add_u32 s26, s66, 0x1bc0c00
	s_addc_u32 s27, s67, 0
	s_add_u32 s28, s66, 0x1bc0d00
	s_addc_u32 s29, s67, 0
	s_add_u32 s30, s66, 0x1bc0e00
	s_addc_u32 s31, s67, 0
	s_add_u32 s34, s66, 0x1bc0f00
	s_addc_u32 s35, s67, 0
	s_add_u32 s36, s66, 0x1bc1000
	s_addc_u32 s37, s67, 0
	s_add_u32 s38, s66, 0x1bc1100
	s_addc_u32 s39, s67, 0
	s_add_u32 s40, s66, 0x1bc1200
	s_addc_u32 s41, s67, 0
	s_add_u32 s42, s66, 0x1bc1300
	s_mul_i32 s33, s33, s70
	s_addc_u32 s43, s67, 0
	s_branch .LBB0_1299

.LBB0_1439:
	s_cmp_lt_i32 s68, 13
	s_cselect_b64 s[6:7], -1, 0
	s_and_b64 s[6:7], s[6:7], s[4:5]
	s_andn2_b64 vcc, exec, s[6:7]
	s_cbranch_vccnz .LBB0_1459
	v_cmp_gt_u32_e32 vcc, 0x100, v1
	s_cbranch_vccz .Lgprio_13
	s_setprio 1
.Lgprio_13:
	v_lshrrev_b32_e32 v146, 1, v1
	v_lshlrev_b32_e32 v147, 2, v1
	s_cmpk_lg_i32 s70, 0x100
	s_cselect_b64 s[4:5], -1, 0
	s_add_i32 s8, s2, 0xfffffed0
	s_cmp_lt_u32 s8, 0xffffff50
	s_cselect_b64 s[8:9], -1, 0
	s_or_b64 s[4:5], s[8:9], s[4:5]
	s_and_b64 vcc, exec, s[4:5]
	s_cbranch_vccnz .Lp12_noconv
	s_load_dwordx2 s[4:5], s[0:1], 0xd8
	v_and_b32_e32 v2, 0xfc, v147
	v_lshlrev_b32_e32 v2, 2, v2
	v_mov_b32_e32 v3, 0
	v_lshrrev_b32_e32 v8, 6, v1
	s_waitcnt lgkmcnt(0)
	v_lshl_add_u64 v[4:5], s[4:5], 0, v[2:3]
	v_add_u32_e32 v6, 0, v2
	v_lshlrev_b32_e32 v2, 5, v1
	s_add_u32 s8, s66, 0xe800000
	v_mul_u32_u24_e32 v7, 0x404, v8
	v_and_b32_e32 v2, 32, v2
	s_addc_u32 s9, s67, 0
	v_lshl_add_u32 v24, v146, 2, 0
	v_mul_u32_u24_e32 v25, 0x404, v2
	s_lshl_b32 s4, s2, 8
	v_add_u32_e32 v9, v6, v7
	s_add_i32 s10, s2, 0xffffff00
	s_add_i32 s11, s4, 0xffff8000
	s_mov_b32 s12, 0x8000
	s_mov_b32 s13, 0x18000
	s_mov_b32 s14, 0x28000
	s_mov_b32 s15, 0x38000
	v_add_u32_e32 v10, 0x2020, v9
	v_add_u32_e32 v11, 0x2028, v9
	v_add_u32_e32 v12, 0x4040, v9
	v_add_u32_e32 v13, 0x4048, v9
	v_add_u32_e32 v14, 0x6060, v9
	v_add_u32_e32 v15, 0x6068, v9
	v_add_u32_e32 v16, 0x8080, v9
	v_add_u32_e32 v17, 0x8088, v9
	v_add_u32_e32 v18, 0xa0a0, v9
	v_add_u32_e32 v19, 0xa0a8, v9
	v_add_u32_e32 v20, 0xc0c0, v9
	v_add_u32_e32 v21, 0xc0c8, v9
	v_add_u32_e32 v22, 0xe0e0, v9
	v_add_u32_e32 v23, 0xe0e8, v9
	s_movk_i32 s16, 0x1600
	v_mov_b64_e32 v[6:7], s[8:9]
	v_lshlrev_b32_e32 v2, 1, v2
	v_add_u32_e32 v24, v24, v25

.LBB0_1456:
.LBB0_1459:
	s_setprio 0
	s_cmp_gt_i32 s69, 13
	s_cselect_b64 s[4:5], -1, 0
	s_and_b64 s[6:7], s[6:7], s[4:5]
	s_andn2_b64 vcc, exec, s[6:7]
	s_cbranch_vccnz .LBB0_1527
	s_cmpk_lt_u32 s69, 0x3e9
	s_mov_b64 s[6:7], -1
	s_cbranch_scc0 .LBB0_1514
	s_waitcnt vmcnt(0)
	s_waitcnt vmcnt(0)
	s_barrier
	s_mov_b64 s[6:7], exec
	v_readlane_b32 s8, v240, 4
	v_readlane_b32 s9, v240, 5
	s_and_b64 s[8:9], s[6:7], s[8:9]
	s_mov_b64 exec, s[8:9]
	s_cbranch_execz .LBB0_1513
	s_add_i32 s8, 0, 0x26000
	v_mov_b32_e32 v2, s8
	s_waitcnt vmcnt(0) expcnt(0) lgkmcnt(0)
	ds_read_b32 v4, v2
	s_add_i32 s8, 0, 0x26004
	v_mov_b32_e32 v2, s8
	ds_read_b32 v2, v2
	s_waitcnt lgkmcnt(1)
	v_cmp_ne_u32_e32 vcc, 0, v4
	s_cbranch_vccnz .LBB0_1477
	s_load_dword s8, s[0:1], 0x110
	s_mov_b32 s44, 1
	v_mov_b32_e32 v18, 0
	s_waitcnt lgkmcnt(0)
	s_mul_i32 s33, s71, s8
	s_add_u32 s8, s66, 0x1bc0200
	s_addc_u32 s9, s67, 0
	s_add_u32 s10, s66, 0x1bc0400
	s_addc_u32 s11, s67, 0
	s_add_u32 s12, s66, 0x1bc0500
	s_addc_u32 s13, s67, 0
	s_add_u32 s14, s66, 0x1bc0600
	s_addc_u32 s15, s67, 0
	s_add_u32 s16, s66, 0x1bc0700
	s_addc_u32 s17, s67, 0
	s_add_u32 s18, s66, 0x1bc0800
	s_addc_u32 s19, s67, 0
	s_add_u32 s20, s66, 0x1bc0900
	s_addc_u32 s21, s67, 0
	s_add_u32 s22, s66, 0x1bc0a00
	s_addc_u32 s23, s67, 0
	s_add_u32 s24, s66, 0x1bc0b00
	s_addc_u32 s25, s67, 0
	s_add_u32 s26, s66, 0x1bc0c00
	s_addc_u32 s27, s67, 0
	s_add_u32 s28, s66, 0x1bc0d00
	s_addc_u32 s29, s67, 0
	s_add_u32 s30, s66, 0x1bc0e00
	s_addc_u32 s31, s67, 0
	s_add_u32 s34, s66, 0x1bc0f00
	s_addc_u32 s35, s67, 0
	s_add_u32 s36, s66, 0x1bc1000
	s_addc_u32 s37, s67, 0
	s_add_u32 s38, s66, 0x1bc1100
	s_addc_u32 s39, s67, 0
	s_add_u32 s40, s66, 0x1bc1200
	s_addc_u32 s41, s67, 0
	s_add_u32 s42, s66, 0x1bc1300
	s_mul_i32 s33, s33, s70
	s_addc_u32 s43, s67, 0
	s_branch .LBB0_1465

.LBB0_1527:
	s_cmp_lt_i32 s68, 14
	s_cselect_b64 s[6:7], -1, 0
	s_and_b64 s[6:7], s[6:7], s[4:5]
	s_andn2_b64 vcc, exec, s[6:7]
	s_cbranch_vccnz .LBB0_1548
	v_cmp_gt_u32_e32 vcc, 0x100, v1
	s_cbranch_vccz .Lgprio_14
	s_setprio 1
.Lgprio_14:
	s_cmpk_gt_i32 s2, 0xff
	v_readfirstlane_b32 s4, v1
	s_cbranch_scc1 .LBB0_1548
	s_add_u32 s19, s66, 0x3c00000
	s_addc_u32 s33, s67, 0
	v_lshrrev_b32_e32 v5, 1, v1
	s_add_u32 s46, s66, 0xe800000
	v_and_b32_e32 v12, 24, v5
	v_lshrrev_b32_e32 v5, 5, v1
	s_addc_u32 s47, s67, 0
	v_and_b32_e32 v5, 4, v5
	v_bfe_u32 v6, v1, 2, 2
	s_ashr_i32 s49, s2, 31
	v_lshlrev_b32_e32 v2, 4, v1
	v_and_b32_e32 v3, 32, v1
	v_bfe_u32 v4, v1, 2, 4
	v_or3_b32 v5, v5, v6, v12
	v_lshrrev_b32_e32 v6, 3, v1
	s_movk_i32 s5, 0x70
	s_lshr_b32 s8, s49, 29
	v_bitop3_b32 v10, v2, v3, 48 bitop3:0x6c
	v_and_or_b32 v7, v6, s5, v4
	s_movk_i32 s5, 0x60
	v_add_u32_e32 v2, 0x2000, v2
	s_add_i32 s8, s2, s8
	v_and_or_b32 v6, v6, s5, v5
	v_lshrrev_b32_e32 v2, 7, v2
	s_movk_i32 s5, 0xf0
	s_ashr_i32 s9, s8, 3
	s_and_b32 s8, s8, -8
	v_and_or_b32 v4, v2, s5, v4
	s_movk_i32 s5, 0xe0
	s_lshr_b32 s14, s4, 6
	s_sub_i32 s8, s2, s8
	v_and_or_b32 v2, v2, s5, v5
	s_lshr_b32 s5, s4, 8
	s_lshl_b32 s48, s14, 10
	s_lshl_b32 s11, s8, 5
	s_mul_i32 s10, s8, 33
	s_cmp_lt_i32 s8, 0
	s_cselect_b32 s8, s10, s11
	s_add_i32 s8, s8, s9
	s_ashr_i32 s9, s8, 31
	s_lshr_b32 s9, s9, 28
	s_add_i32 s9, s8, s9
	s_ashr_i32 s10, s9, 4
	s_and_b32 s9, s9, 0xfff0
	s_sub_i32 s8, s8, s9
	s_bfe_i32 s9, s8, 0x80000
	s_bfe_u32 s9, s9, 0x2000d
	s_add_i32 s9, s8, s9
	s_bfe_i32 s11, s9, 0x80000
	s_and_b32 s9, s9, 0xfc
	s_sub_i32 s8, s8, s9
	s_lshl_b32 s10, s10, 2
	s_sext_i32_i8 s8, s8
	s_sext_i32_i16 s11, s11
	s_add_i32 s75, s10, s8
	s_lshr_b32 s16, s11, 2
	s_mul_i32 s9, s75, 0x160000
	s_mul_hi_i32 s8, s75, 0x160000
	s_add_u32 s38, s19, s9
	v_and_b32_e32 v11, 64, v1
	s_addc_u32 s39, s33, s8
	s_ashr_i32 s8, s11, 2
	v_or_b32_e32 v3, v10, v11
	s_mul_hi_i32 s9, s8, 0x160000
	s_mul_i32 s8, s8, 0x160000
	v_lshrrev_b32_e32 v3, 1, v3
	v_mul_u32_u24_e32 v6, 0xb00, v6
	s_add_u32 s40, s46, s8
	v_or_b32_e32 v6, v6, v3
	s_addc_u32 s41, s47, s9
	s_add_i32 s50, s48, 0
	v_lshlrev_b32_e32 v172, 1, v6
	v_mul_u32_u24_e32 v2, 0xb00, v2
	s_add_i32 m0, s50, 0x10000
	v_or_b32_e32 v2, v2, v3
	global_load_lds_dwordx4 v172, s[40:41]
	s_add_i32 m0, s50, 0x12000
	v_lshlrev_b32_e32 v176, 1, v2
	s_add_u32 s8, s40, 0xb0000
	v_mul_u32_u24_e32 v13, 0xb00, v7
	global_load_lds_dwordx4 v176, s[40:41]
	s_addc_u32 s9, s41, 0
	s_add_i32 m0, s50, 0x14000
	v_or_b32_e32 v7, v3, v13
	v_mul_u32_u24_e32 v14, 0xb00, v4
	global_load_lds_dwordx4 v172, s[8:9]
	s_add_i32 m0, s50, 0x16000
	s_add_i32 s51, s50, 0x2000
	v_lshlrev_b32_e32 v170, 1, v7
	v_or_b32_e32 v4, v14, v3
	global_load_lds_dwordx4 v176, s[8:9]
	s_mov_b32 m0, s50
	s_add_u32 s8, s38, 0xb0000
	v_lshlrev_b32_e32 v174, 1, v4
	global_load_lds_dwordx4 v170, s[38:39]
	s_mov_b32 m0, s51
	s_addc_u32 s9, s39, 0
	s_add_i32 s52, s50, 0x4000
	global_load_lds_dwordx4 v174, s[38:39]
	s_mov_b32 m0, s52
	s_add_i32 s53, s50, 0x6000
	global_load_lds_dwordx4 v170, s[8:9]
	s_mov_b32 m0, s53
	v_mov_b32_e32 v173, 0
	global_load_lds_dwordx4 v174, s[8:9]
	v_mov_b32_e32 v177, v173
	v_mov_b32_e32 v171, v173
	v_mov_b32_e32 v175, v173
	s_cmp_eq_u32 s5, 1
	s_mov_b32 s54, 0
	v_lshl_add_u64 v[8:9], s[40:41], 0, v[172:173]
	v_lshl_add_u64 v[6:7], s[40:41], 0, v[176:177]
	v_lshl_add_u64 v[2:3], s[38:39], 0, v[170:171]
	s_cselect_b64 s[8:9], -1, 0
	s_cmp_lg_u32 s5, 1
	v_lshl_add_u64 v[4:5], s[38:39], 0, v[174:175]
	s_cbranch_scc1 .LBB0_1531
	s_barrier

.LBB0_1548:
	s_setprio 0
	s_cmp_gt_i32 s69, 14
	s_cselect_b64 s[4:5], -1, 0
	s_and_b64 s[6:7], s[6:7], s[4:5]
	s_andn2_b64 vcc, exec, s[6:7]
	s_cbranch_vccnz .LBB0_1616
	s_cmpk_lt_u32 s69, 0x3e9
	s_mov_b64 s[6:7], -1
	s_cbranch_scc0 .LBB0_1603
	s_waitcnt vmcnt(0)
	s_waitcnt vmcnt(0)
	s_barrier
	s_mov_b64 s[6:7], exec
	v_readlane_b32 s8, v240, 4
	v_readlane_b32 s9, v240, 5
	s_and_b64 s[8:9], s[6:7], s[8:9]
	s_mov_b64 exec, s[8:9]
	s_cbranch_execz .LBB0_1602
	s_add_i32 s8, 0, 0x26000
	v_mov_b32_e32 v2, s8
	s_waitcnt vmcnt(0) expcnt(0) lgkmcnt(0)
	ds_read_b32 v4, v2
	s_add_i32 s8, 0, 0x26004
	v_mov_b32_e32 v2, s8
	ds_read_b32 v2, v2
	s_waitcnt lgkmcnt(1)
	v_cmp_ne_u32_e32 vcc, 0, v4
	s_cbranch_vccnz .LBB0_1566
	s_load_dword s8, s[0:1], 0x110
	s_mov_b32 s46, 1
	v_mov_b32_e32 v18, 0
	s_waitcnt lgkmcnt(0)
	s_mul_i32 s33, s71, s8
	s_add_u32 s8, s66, 0x1bc0200
	s_addc_u32 s9, s67, 0
	s_add_u32 s10, s66, 0x1bc0400
	s_addc_u32 s11, s67, 0
	s_add_u32 s12, s66, 0x1bc0500
	s_addc_u32 s13, s67, 0
	s_add_u32 s14, s66, 0x1bc0600
	s_addc_u32 s15, s67, 0
	s_add_u32 s16, s66, 0x1bc0700
	s_addc_u32 s17, s67, 0
	s_add_u32 s18, s66, 0x1bc0800
	s_addc_u32 s19, s67, 0
	s_add_u32 s20, s66, 0x1bc0900
	s_addc_u32 s21, s67, 0
	s_add_u32 s22, s66, 0x1bc0a00
	s_addc_u32 s23, s67, 0
	s_add_u32 s24, s66, 0x1bc0b00
	s_addc_u32 s25, s67, 0
	s_add_u32 s26, s66, 0x1bc0c00
	s_addc_u32 s27, s67, 0
	s_add_u32 s28, s66, 0x1bc0d00
	s_addc_u32 s29, s67, 0
	s_add_u32 s30, s66, 0x1bc0e00
	s_addc_u32 s31, s67, 0
	s_add_u32 s34, s66, 0x1bc0f00
	s_addc_u32 s35, s67, 0
	s_add_u32 s36, s66, 0x1bc1000
	s_addc_u32 s37, s67, 0
	s_add_u32 s38, s66, 0x1bc1100
	s_addc_u32 s39, s67, 0
	s_add_u32 s40, s66, 0x1bc1200
	s_addc_u32 s41, s67, 0
	s_add_u32 s42, s66, 0x1bc1300
	s_mul_i32 s33, s33, s70
	s_addc_u32 s43, s67, 0
	s_branch .LBB0_1554
